# combo2 minus the compiler's duplicate lgkmcnt(0) right after each pre-MMA barrier in the three GEMM loops
# baseline (speedup 1.0000x reference)
.LBB0_143:
	s_add_u32 s26, s16, 0xfffc0080
	s_addc_u32 s27, s17, -1
	s_add_i32 s34, 0, 0x10000
	s_cmp_eq_u32 s37, 12
	s_cselect_b32 s31, s9, s27
	s_cselect_b32 s30, s25, s26
	v_add_u32_e32 v138, s34, v141
	s_cselect_b32 s27, s7, s36
	s_cselect_b32 s26, s28, s29
	s_add_i32 s40, 0, 0x14000
	ds_read_b128 v[144:147], v138
	ds_read_b128 v[148:151], v138 offset:1024
	ds_read_b128 v[152:155], v138 offset:2048
	ds_read_b128 v[156:159], v138 offset:3072
	v_add_u32_e32 v138, s40, v141
	ds_read_b128 v[160:163], v138
	ds_read_b128 v[164:167], v138 offset:1024
	ds_read_b128 v[168:171], v138 offset:2048
	ds_read_b128 v[172:175], v138 offset:3072
	v_lshl_add_u64 v[138:139], s[16:17], 0, v[132:133]
	s_add_i32 m0, s53, 0xc000
	ds_read_b128 v[176:179], v143
	ds_read_b128 v[180:183], v143 offset:1024
	ds_read_b128 v[184:187], v143 offset:2048
	ds_read_b128 v[188:191], v143 offset:3072
	ds_read_b128 v[192:195], v143 offset:4096
	ds_read_b128 v[196:199], v143 offset:5120
	ds_read_b128 v[200:203], v143 offset:6144
	ds_read_b128 v[204:207], v143 offset:7168
	global_load_lds_dwordx4 v[138:139], off
	v_lshl_add_u64 v[138:139], s[16:17], 0, v[134:135]
	s_add_i32 m0, s53, 0xe000
	s_nop 0
	global_load_lds_dwordx4 v[138:139], off
	s_waitcnt vmcnt(8)
	s_waitcnt lgkmcnt(0)
	s_barrier
	s_setprio 1
	v_mfma_f32_16x16x32_bf16 v[126:129], v[144:147], v[176:179], v[126:129]
	v_mfma_f32_16x16x32_bf16 v[126:129], v[148:151], v[180:183], v[126:129]
	v_mfma_f32_16x16x32_bf16 v[118:121], v[152:155], v[176:179], v[118:121]
	v_mfma_f32_16x16x32_bf16 v[118:121], v[156:159], v[180:183], v[118:121]
	v_mfma_f32_16x16x32_bf16 v[110:113], v[144:147], v[184:187], v[110:113]
	v_mfma_f32_16x16x32_bf16 v[110:113], v[148:151], v[188:191], v[110:113]
	v_mfma_f32_16x16x32_bf16 v[102:105], v[152:155], v[184:187], v[102:105]
	v_mfma_f32_16x16x32_bf16 v[102:105], v[156:159], v[188:191], v[102:105]
	v_mfma_f32_16x16x32_bf16 v[94:97], v[144:147], v[192:195], v[94:97]
	v_mfma_f32_16x16x32_bf16 v[94:97], v[148:151], v[196:199], v[94:97]
	v_mfma_f32_16x16x32_bf16 v[86:89], v[152:155], v[192:195], v[86:89]
	v_mfma_f32_16x16x32_bf16 v[86:89], v[156:159], v[196:199], v[86:89]
	v_mfma_f32_16x16x32_bf16 v[78:81], v[144:147], v[200:203], v[78:81]
	v_mfma_f32_16x16x32_bf16 v[78:81], v[148:151], v[204:207], v[78:81]
	v_mfma_f32_16x16x32_bf16 v[70:73], v[152:155], v[200:203], v[70:73]
	v_mfma_f32_16x16x32_bf16 v[70:73], v[156:159], v[204:207], v[70:73]
	s_setprio 0
	s_setprio 1
	v_mfma_f32_16x16x32_bf16 v[122:125], v[160:163], v[176:179], v[122:125]
	v_mfma_f32_16x16x32_bf16 v[122:125], v[164:167], v[180:183], v[122:125]
	v_mfma_f32_16x16x32_bf16 v[114:117], v[168:171], v[176:179], v[114:117]
	v_mfma_f32_16x16x32_bf16 v[114:117], v[172:175], v[180:183], v[114:117]
	v_mfma_f32_16x16x32_bf16 v[106:109], v[160:163], v[184:187], v[106:109]
	v_mfma_f32_16x16x32_bf16 v[106:109], v[164:167], v[188:191], v[106:109]
	v_mfma_f32_16x16x32_bf16 v[98:101], v[168:171], v[184:187], v[98:101]
	v_mfma_f32_16x16x32_bf16 v[98:101], v[172:175], v[188:191], v[98:101]
	v_mfma_f32_16x16x32_bf16 v[90:93], v[160:163], v[192:195], v[90:93]
	v_mfma_f32_16x16x32_bf16 v[90:93], v[164:167], v[196:199], v[90:93]
	v_mfma_f32_16x16x32_bf16 v[82:85], v[168:171], v[192:195], v[82:85]
	v_mfma_f32_16x16x32_bf16 v[82:85], v[172:175], v[196:199], v[82:85]
	s_setprio 3
	s_barrier
	v_mfma_f32_16x16x32_bf16 v[74:77], v[160:163], v[200:203], v[74:77]
	v_mfma_f32_16x16x32_bf16 v[74:77], v[164:167], v[204:207], v[74:77]
	v_mfma_f32_16x16x32_bf16 v[66:69], v[168:171], v[200:203], v[66:69]
	v_mfma_f32_16x16x32_bf16 v[66:69], v[172:175], v[204:207], v[66:69]
	s_setprio 0
	s_add_i32 s34, s34, s47
	v_lshl_add_u64 v[138:139], s[26:27], 0, v[0:1]
	s_mov_b32 m0, s34
	ds_read_b128 v[176:179], v143 offset:16384
	ds_read_b128 v[180:183], v143 offset:17408
	ds_read_b128 v[184:187], v143 offset:18432
	ds_read_b128 v[188:191], v143 offset:19456
	ds_read_b128 v[192:195], v143 offset:20480
	ds_read_b128 v[196:199], v143 offset:21504
	ds_read_b128 v[200:203], v143 offset:22528
	ds_read_b128 v[204:207], v143 offset:23552
	global_load_lds_dwordx4 v[138:139], off
	s_add_i32 m0, s34, 0x2000
	s_add_u32 s34, s26, 0x40000
	v_lshl_add_u64 v[208:209], s[26:27], 0, v[130:131]
	s_addc_u32 s35, s27, 0
	s_add_i32 s40, s40, s47
	global_load_lds_dwordx4 v[208:209], off
	v_lshl_add_u64 v[222:223], s[34:35], 0, v[0:1]
	s_mov_b32 m0, s40
	v_lshl_add_u64 v[224:225], s[30:31], 0, v[130:131]
	global_load_lds_dwordx4 v[222:223], off
	v_lshl_add_u64 v[222:223], s[34:35], 0, v[130:131]
	s_add_i32 m0, s40, 0x2000
	s_nop 0
	global_load_lds_dwordx4 v[222:223], off
	v_lshl_add_u64 v[222:223], s[30:31], 0, v[0:1]
	s_mov_b32 m0, s53
	s_nop 0
	global_load_lds_dwordx4 v[222:223], off
	s_mov_b32 m0, s64
	s_nop 0
	global_load_lds_dwordx4 v[224:225], off
	s_waitcnt vmcnt(8)
	s_waitcnt lgkmcnt(0)
	s_barrier
	s_setprio 1
	v_mfma_f32_16x16x32_bf16 v[62:65], v[144:147], v[176:179], v[62:65]
	v_mfma_f32_16x16x32_bf16 v[62:65], v[148:151], v[180:183], v[62:65]
	v_mfma_f32_16x16x32_bf16 v[54:57], v[152:155], v[176:179], v[54:57]
	v_mfma_f32_16x16x32_bf16 v[54:57], v[156:159], v[180:183], v[54:57]
	v_mfma_f32_16x16x32_bf16 v[46:49], v[144:147], v[184:187], v[46:49]
	v_mfma_f32_16x16x32_bf16 v[46:49], v[148:151], v[188:191], v[46:49]
	v_mfma_f32_16x16x32_bf16 v[38:41], v[152:155], v[184:187], v[38:41]
	v_mfma_f32_16x16x32_bf16 v[38:41], v[156:159], v[188:191], v[38:41]
	v_mfma_f32_16x16x32_bf16 v[30:33], v[144:147], v[192:195], v[30:33]
	v_mfma_f32_16x16x32_bf16 v[30:33], v[148:151], v[196:199], v[30:33]
	v_mfma_f32_16x16x32_bf16 v[22:25], v[152:155], v[192:195], v[22:25]
	v_mfma_f32_16x16x32_bf16 v[22:25], v[156:159], v[196:199], v[22:25]
	v_mfma_f32_16x16x32_bf16 v[14:17], v[144:147], v[200:203], v[14:17]
	v_mfma_f32_16x16x32_bf16 v[14:17], v[148:151], v[204:207], v[14:17]
	v_mfma_f32_16x16x32_bf16 v[6:9], v[152:155], v[200:203], v[6:9]
	v_mfma_f32_16x16x32_bf16 v[6:9], v[156:159], v[204:207], v[6:9]
	s_setprio 0
	s_setprio 1
	v_mfma_f32_16x16x32_bf16 v[58:61], v[160:163], v[176:179], v[58:61]
	v_mfma_f32_16x16x32_bf16 v[58:61], v[164:167], v[180:183], v[58:61]
	v_mfma_f32_16x16x32_bf16 v[50:53], v[168:171], v[176:179], v[50:53]
	v_mfma_f32_16x16x32_bf16 v[50:53], v[172:175], v[180:183], v[50:53]
	v_mfma_f32_16x16x32_bf16 v[42:45], v[160:163], v[184:187], v[42:45]
	v_mfma_f32_16x16x32_bf16 v[42:45], v[164:167], v[188:191], v[42:45]
	v_mfma_f32_16x16x32_bf16 v[34:37], v[168:171], v[184:187], v[34:37]
	v_mfma_f32_16x16x32_bf16 v[34:37], v[172:175], v[188:191], v[34:37]
	v_mfma_f32_16x16x32_bf16 v[26:29], v[160:163], v[192:195], v[26:29]
	v_mfma_f32_16x16x32_bf16 v[26:29], v[164:167], v[196:199], v[26:29]
	v_mfma_f32_16x16x32_bf16 v[18:21], v[168:171], v[192:195], v[18:21]
	v_mfma_f32_16x16x32_bf16 v[18:21], v[172:175], v[196:199], v[18:21]
	s_setprio 3
	s_barrier
	v_mfma_f32_16x16x32_bf16 v[10:13], v[160:163], v[200:203], v[10:13]
	v_mfma_f32_16x16x32_bf16 v[10:13], v[164:167], v[204:207], v[10:13]
	v_mfma_f32_16x16x32_bf16 v[2:5], v[168:171], v[200:203], v[2:5]
	v_mfma_f32_16x16x32_bf16 v[2:5], v[172:175], v[204:207], v[2:5]
	s_setprio 0
	s_add_i32 s34, 0, 0x18000
	s_add_i32 s35, 0, 0x1c000
	v_add_u32_e32 v156, s34, v141
	v_add_u32_e32 v172, s35, v141
	ds_read_b128 v[144:147], v156
	ds_read_b128 v[148:151], v156 offset:1024
	ds_read_b128 v[152:155], v156 offset:2048
	ds_read_b128 v[156:159], v156 offset:3072
	ds_read_b128 v[160:163], v172
	ds_read_b128 v[164:167], v172 offset:1024
	ds_read_b128 v[168:171], v172 offset:2048
	ds_read_b128 v[172:175], v172 offset:3072
	s_add_u32 s30, s30, 0x40000
	s_addc_u32 s31, s31, 0
	s_mov_b32 m0, s65
	v_lshl_add_u64 v[226:227], s[30:31], 0, v[0:1]
	ds_read_b128 v[176:179], v143 offset:32768
	ds_read_b128 v[180:183], v143 offset:33792
	ds_read_b128 v[184:187], v143 offset:34816
	ds_read_b128 v[188:191], v143 offset:35840
	ds_read_b128 v[192:195], v143 offset:36864
	ds_read_b128 v[196:199], v143 offset:37888
	ds_read_b128 v[200:203], v143 offset:38912
	ds_read_b128 v[204:207], v143 offset:39936
	global_load_lds_dwordx4 v[226:227], off
	v_lshl_add_u64 v[226:227], s[30:31], 0, v[130:131]
	s_mov_b32 m0, s68
	s_nop 0
	global_load_lds_dwordx4 v[226:227], off
	s_waitcnt vmcnt(8)
	s_waitcnt lgkmcnt(0)
	s_barrier
	s_setprio 1
	v_mfma_f32_16x16x32_bf16 v[126:129], v[144:147], v[176:179], v[126:129]
	v_mfma_f32_16x16x32_bf16 v[126:129], v[148:151], v[180:183], v[126:129]
	v_mfma_f32_16x16x32_bf16 v[118:121], v[152:155], v[176:179], v[118:121]
	v_mfma_f32_16x16x32_bf16 v[118:121], v[156:159], v[180:183], v[118:121]
	v_mfma_f32_16x16x32_bf16 v[110:113], v[144:147], v[184:187], v[110:113]
	v_mfma_f32_16x16x32_bf16 v[110:113], v[148:151], v[188:191], v[110:113]
	v_mfma_f32_16x16x32_bf16 v[102:105], v[152:155], v[184:187], v[102:105]
	v_mfma_f32_16x16x32_bf16 v[102:105], v[156:159], v[188:191], v[102:105]
	v_mfma_f32_16x16x32_bf16 v[94:97], v[144:147], v[192:195], v[94:97]
	v_mfma_f32_16x16x32_bf16 v[94:97], v[148:151], v[196:199], v[94:97]
	v_mfma_f32_16x16x32_bf16 v[86:89], v[152:155], v[192:195], v[86:89]
	v_mfma_f32_16x16x32_bf16 v[86:89], v[156:159], v[196:199], v[86:89]
	v_mfma_f32_16x16x32_bf16 v[78:81], v[144:147], v[200:203], v[78:81]
	v_mfma_f32_16x16x32_bf16 v[78:81], v[148:151], v[204:207], v[78:81]
	v_mfma_f32_16x16x32_bf16 v[70:73], v[152:155], v[200:203], v[70:73]
	v_mfma_f32_16x16x32_bf16 v[70:73], v[156:159], v[204:207], v[70:73]
	s_setprio 0
	s_setprio 1
	v_mfma_f32_16x16x32_bf16 v[122:125], v[160:163], v[176:179], v[122:125]
	v_mfma_f32_16x16x32_bf16 v[122:125], v[164:167], v[180:183], v[122:125]
	v_mfma_f32_16x16x32_bf16 v[114:117], v[168:171], v[176:179], v[114:117]
	v_mfma_f32_16x16x32_bf16 v[114:117], v[172:175], v[180:183], v[114:117]
	v_mfma_f32_16x16x32_bf16 v[106:109], v[160:163], v[184:187], v[106:109]
	v_mfma_f32_16x16x32_bf16 v[106:109], v[164:167], v[188:191], v[106:109]
	v_mfma_f32_16x16x32_bf16 v[98:101], v[168:171], v[184:187], v[98:101]
	v_mfma_f32_16x16x32_bf16 v[98:101], v[172:175], v[188:191], v[98:101]
	v_mfma_f32_16x16x32_bf16 v[90:93], v[160:163], v[192:195], v[90:93]
	v_mfma_f32_16x16x32_bf16 v[90:93], v[164:167], v[196:199], v[90:93]
	v_mfma_f32_16x16x32_bf16 v[82:85], v[168:171], v[192:195], v[82:85]
	v_mfma_f32_16x16x32_bf16 v[82:85], v[172:175], v[196:199], v[82:85]
	s_setprio 3
	s_barrier
	v_mfma_f32_16x16x32_bf16 v[74:77], v[160:163], v[200:203], v[74:77]
	v_mfma_f32_16x16x32_bf16 v[74:77], v[164:167], v[204:207], v[74:77]
	v_mfma_f32_16x16x32_bf16 v[66:69], v[168:171], v[200:203], v[66:69]
	v_mfma_f32_16x16x32_bf16 v[66:69], v[172:175], v[204:207], v[66:69]
	s_setprio 0
	s_add_i32 s30, s34, s47
	v_lshl_add_u64 v[138:139], v[138:139], 0, s[22:23]
	s_mov_b32 m0, s30
	ds_read_b128 v[176:179], v143 offset:49152
	ds_read_b128 v[180:183], v143 offset:50176
	ds_read_b128 v[184:187], v143 offset:51200
	ds_read_b128 v[188:191], v143 offset:52224
	ds_read_b128 v[192:195], v143 offset:53248
	ds_read_b128 v[196:199], v143 offset:54272
	ds_read_b128 v[200:203], v143 offset:55296
	ds_read_b128 v[204:207], v143 offset:56320
	global_load_lds_dwordx4 v[138:139], off
	s_add_i32 m0, s30, 0x2000
	s_add_u32 s26, s26, 0x40080
	v_lshl_add_u64 v[138:139], v[208:209], 0, s[22:23]
	s_addc_u32 s27, s27, 0
	s_add_i32 s30, s35, s47
	global_load_lds_dwordx4 v[138:139], off
	v_lshl_add_u64 v[138:139], s[26:27], 0, v[0:1]
	s_mov_b32 m0, s30
	s_nop 0
	global_load_lds_dwordx4 v[138:139], off
	v_lshl_add_u64 v[138:139], s[26:27], 0, v[130:131]
	s_add_i32 m0, s30, 0x2000
	s_nop 0
	global_load_lds_dwordx4 v[138:139], off
	v_lshl_add_u64 v[138:139], v[222:223], 0, s[22:23]
	s_mov_b32 m0, s69
	s_nop 0
	global_load_lds_dwordx4 v[138:139], off
	v_lshl_add_u64 v[138:139], v[224:225], 0, s[22:23]
	s_mov_b32 m0, s70
	s_nop 0
	global_load_lds_dwordx4 v[138:139], off
	s_waitcnt vmcnt(8)
	s_waitcnt lgkmcnt(0)
	s_barrier
	s_setprio 1
	v_mfma_f32_16x16x32_bf16 v[62:65], v[144:147], v[176:179], v[62:65]
	v_mfma_f32_16x16x32_bf16 v[62:65], v[148:151], v[180:183], v[62:65]
	v_mfma_f32_16x16x32_bf16 v[54:57], v[152:155], v[176:179], v[54:57]
	v_mfma_f32_16x16x32_bf16 v[54:57], v[156:159], v[180:183], v[54:57]
	v_mfma_f32_16x16x32_bf16 v[46:49], v[144:147], v[184:187], v[46:49]
	v_mfma_f32_16x16x32_bf16 v[46:49], v[148:151], v[188:191], v[46:49]
	v_mfma_f32_16x16x32_bf16 v[38:41], v[152:155], v[184:187], v[38:41]
	v_mfma_f32_16x16x32_bf16 v[38:41], v[156:159], v[188:191], v[38:41]
	v_mfma_f32_16x16x32_bf16 v[30:33], v[144:147], v[192:195], v[30:33]
	v_mfma_f32_16x16x32_bf16 v[30:33], v[148:151], v[196:199], v[30:33]
	v_mfma_f32_16x16x32_bf16 v[22:25], v[152:155], v[192:195], v[22:25]
	v_mfma_f32_16x16x32_bf16 v[22:25], v[156:159], v[196:199], v[22:25]
	v_mfma_f32_16x16x32_bf16 v[14:17], v[144:147], v[200:203], v[14:17]
	v_mfma_f32_16x16x32_bf16 v[14:17], v[148:151], v[204:207], v[14:17]
	v_mfma_f32_16x16x32_bf16 v[6:9], v[152:155], v[200:203], v[6:9]
	v_mfma_f32_16x16x32_bf16 v[6:9], v[156:159], v[204:207], v[6:9]
	s_setprio 0
	s_setprio 1
	v_mfma_f32_16x16x32_bf16 v[58:61], v[160:163], v[176:179], v[58:61]
	v_mfma_f32_16x16x32_bf16 v[58:61], v[164:167], v[180:183], v[58:61]
	v_mfma_f32_16x16x32_bf16 v[50:53], v[168:171], v[176:179], v[50:53]
	v_mfma_f32_16x16x32_bf16 v[50:53], v[172:175], v[180:183], v[50:53]
	v_mfma_f32_16x16x32_bf16 v[42:45], v[160:163], v[184:187], v[42:45]
	v_mfma_f32_16x16x32_bf16 v[42:45], v[164:167], v[188:191], v[42:45]
	v_mfma_f32_16x16x32_bf16 v[34:37], v[168:171], v[184:187], v[34:37]
	v_mfma_f32_16x16x32_bf16 v[34:37], v[172:175], v[188:191], v[34:37]
	v_mfma_f32_16x16x32_bf16 v[26:29], v[160:163], v[192:195], v[26:29]
	v_mfma_f32_16x16x32_bf16 v[26:29], v[164:167], v[196:199], v[26:29]
	v_mfma_f32_16x16x32_bf16 v[18:21], v[168:171], v[192:195], v[18:21]
	v_mfma_f32_16x16x32_bf16 v[18:21], v[172:175], v[196:199], v[18:21]
	s_setprio 3
	s_barrier
	v_mfma_f32_16x16x32_bf16 v[10:13], v[160:163], v[200:203], v[10:13]
	v_mfma_f32_16x16x32_bf16 v[10:13], v[164:167], v[204:207], v[10:13]
	v_mfma_f32_16x16x32_bf16 v[2:5], v[168:171], v[200:203], v[2:5]
	v_mfma_f32_16x16x32_bf16 v[2:5], v[172:175], v[204:207], v[2:5]
	s_setprio 0
	s_add_i32 s37, s37, 2
	s_add_u32 s16, s16, 0x100
	s_addc_u32 s17, s17, 0
	s_add_u32 s29, s29, 0x100
	s_addc_u32 s36, s36, 0
	s_cmp_gt_u32 s37, 13
	s_cbranch_scc0 .LBB0_143
	s_and_b64 vcc, exec, s[2:3]
	s_cbranch_vccz .LBB0_146
	s_barrier

.LBB0_233:
	s_add_u32 s4, s0, 0xfffc0080
	s_addc_u32 s5, s1, -1
	s_add_i32 s18, 0, 0x10000
	s_cmp_eq_u32 s17, 12
	s_cselect_b32 s9, s3, s5
	s_cselect_b32 s8, s11, s4
	v_add_u32_e32 v0, s18, v191
	s_cselect_b32 s5, s12, s15
	s_cselect_b32 s4, s13, s14
	s_add_i32 s25, 0, 0x14000
	ds_read_b128 v[2:5], v0
	ds_read_b128 v[6:9], v0 offset:1024
	ds_read_b128 v[10:13], v0 offset:2048
	ds_read_b128 v[14:17], v0 offset:3072
	v_add_u32_e32 v0, s25, v191
	ds_read_b128 v[146:149], v0
	ds_read_b128 v[150:153], v0 offset:1024
	ds_read_b128 v[154:157], v0 offset:2048
	ds_read_b128 v[158:161], v0 offset:3072
	v_lshl_add_u64 v[230:231], s[0:1], 0, v[178:179]
	s_add_i32 m0, s65, 0xc000
	ds_read_b128 v[162:165], v200
	ds_read_b128 v[166:169], v200 offset:1024
	ds_read_b128 v[182:185], v200 offset:2048
	ds_read_b128 v[186:189], v200 offset:3072
	ds_read_b128 v[202:205], v200 offset:4096
	ds_read_b128 v[206:209], v200 offset:5120
	ds_read_b128 v[222:225], v200 offset:6144
	ds_read_b128 v[226:229], v200 offset:7168
	global_load_lds_dwordx4 v[230:231], off
	v_lshl_add_u64 v[230:231], s[0:1], 0, v[180:181]
	s_add_i32 m0, s65, 0xe000
	s_nop 0
	global_load_lds_dwordx4 v[230:231], off
	s_waitcnt vmcnt(8)
	s_waitcnt lgkmcnt(0)
	s_barrier
	s_setprio 1
	v_mfma_f32_16x16x32_bf16 v[142:145], v[2:5], v[162:165], v[142:145]
	v_mfma_f32_16x16x32_bf16 v[142:145], v[6:9], v[166:169], v[142:145]
	v_mfma_f32_16x16x32_bf16 v[138:141], v[10:13], v[162:165], v[138:141]
	v_mfma_f32_16x16x32_bf16 v[138:141], v[14:17], v[166:169], v[138:141]
	v_mfma_f32_16x16x32_bf16 v[134:137], v[2:5], v[182:185], v[134:137]
	v_mfma_f32_16x16x32_bf16 v[134:137], v[6:9], v[186:189], v[134:137]
	v_mfma_f32_16x16x32_bf16 v[126:129], v[10:13], v[182:185], v[126:129]
	v_mfma_f32_16x16x32_bf16 v[126:129], v[14:17], v[186:189], v[126:129]
	v_mfma_f32_16x16x32_bf16 v[118:121], v[2:5], v[202:205], v[118:121]
	v_mfma_f32_16x16x32_bf16 v[118:121], v[6:9], v[206:209], v[118:121]
	v_mfma_f32_16x16x32_bf16 v[110:113], v[10:13], v[202:205], v[110:113]
	v_mfma_f32_16x16x32_bf16 v[110:113], v[14:17], v[206:209], v[110:113]
	v_mfma_f32_16x16x32_bf16 v[102:105], v[2:5], v[222:225], v[102:105]
	v_mfma_f32_16x16x32_bf16 v[102:105], v[6:9], v[226:229], v[102:105]
	v_mfma_f32_16x16x32_bf16 v[94:97], v[10:13], v[222:225], v[94:97]
	v_mfma_f32_16x16x32_bf16 v[94:97], v[14:17], v[226:229], v[94:97]
	s_setprio 0
	s_setprio 1
	v_mfma_f32_16x16x32_bf16 v[130:133], v[146:149], v[162:165], v[130:133]
	v_mfma_f32_16x16x32_bf16 v[130:133], v[150:153], v[166:169], v[130:133]
	v_mfma_f32_16x16x32_bf16 v[122:125], v[154:157], v[162:165], v[122:125]
	v_mfma_f32_16x16x32_bf16 v[122:125], v[158:161], v[166:169], v[122:125]
	v_mfma_f32_16x16x32_bf16 v[114:117], v[146:149], v[182:185], v[114:117]
	v_mfma_f32_16x16x32_bf16 v[114:117], v[150:153], v[186:189], v[114:117]
	v_mfma_f32_16x16x32_bf16 v[106:109], v[154:157], v[182:185], v[106:109]
	v_mfma_f32_16x16x32_bf16 v[106:109], v[158:161], v[186:189], v[106:109]
	v_mfma_f32_16x16x32_bf16 v[98:101], v[146:149], v[202:205], v[98:101]
	v_mfma_f32_16x16x32_bf16 v[98:101], v[150:153], v[206:209], v[98:101]
	v_mfma_f32_16x16x32_bf16 v[90:93], v[154:157], v[202:205], v[90:93]
	v_mfma_f32_16x16x32_bf16 v[90:93], v[158:161], v[206:209], v[90:93]
	s_setprio 3
	s_barrier
	v_mfma_f32_16x16x32_bf16 v[86:89], v[146:149], v[222:225], v[86:89]
	v_mfma_f32_16x16x32_bf16 v[86:89], v[150:153], v[226:229], v[86:89]
	v_mfma_f32_16x16x32_bf16 v[82:85], v[154:157], v[222:225], v[82:85]
	v_mfma_f32_16x16x32_bf16 v[82:85], v[158:161], v[226:229], v[82:85]
	s_setprio 0
	s_add_i32 s18, s18, s64
	v_lshl_add_u64 v[230:231], s[4:5], 0, v[172:173]
	s_mov_b32 m0, s18
	ds_read_b128 v[162:165], v200 offset:16384
	ds_read_b128 v[166:169], v200 offset:17408
	ds_read_b128 v[182:185], v200 offset:18432
	ds_read_b128 v[186:189], v200 offset:19456
	ds_read_b128 v[202:205], v200 offset:20480
	ds_read_b128 v[206:209], v200 offset:21504
	ds_read_b128 v[222:225], v200 offset:22528
	ds_read_b128 v[226:229], v200 offset:23552
	global_load_lds_dwordx4 v[230:231], off
	s_add_i32 m0, s18, 0x2000
	s_add_u32 s18, s4, 0x40000
	v_lshl_add_u64 v[232:233], s[4:5], 0, v[170:171]
	s_addc_u32 s19, s5, 0
	s_add_i32 s25, s25, s64
	global_load_lds_dwordx4 v[232:233], off
	v_lshl_add_u64 v[246:247], s[18:19], 0, v[172:173]
	s_mov_b32 m0, s25
	v_lshl_add_u64 v[248:249], s[8:9], 0, v[170:171]
	global_load_lds_dwordx4 v[246:247], off
	v_lshl_add_u64 v[246:247], s[18:19], 0, v[170:171]
	s_add_i32 m0, s25, 0x2000
	s_nop 0
	global_load_lds_dwordx4 v[246:247], off
	v_lshl_add_u64 v[246:247], s[8:9], 0, v[172:173]
	s_mov_b32 m0, s65
	s_nop 0
	global_load_lds_dwordx4 v[246:247], off
	s_mov_b32 m0, s68
	s_nop 0
	global_load_lds_dwordx4 v[248:249], off
	s_waitcnt vmcnt(8)
	s_waitcnt lgkmcnt(0)
	s_barrier
	s_setprio 1
	v_mfma_f32_16x16x32_bf16 v[78:81], v[2:5], v[162:165], v[78:81]
	v_mfma_f32_16x16x32_bf16 v[74:77], v[10:13], v[162:165], v[74:77]
	v_mfma_f32_16x16x32_bf16 v[70:73], v[2:5], v[182:185], v[70:73]
	v_mfma_f32_16x16x32_bf16 v[62:65], v[10:13], v[182:185], v[62:65]
	v_mfma_f32_16x16x32_bf16 v[54:57], v[2:5], v[202:205], v[54:57]
	v_mfma_f32_16x16x32_bf16 v[46:49], v[10:13], v[202:205], v[46:49]
	v_mfma_f32_16x16x32_bf16 v[2:5], v[2:5], v[222:225], v[38:41]
	v_mfma_f32_16x16x32_bf16 v[78:81], v[6:9], v[166:169], v[78:81]
	v_mfma_f32_16x16x32_bf16 v[74:77], v[14:17], v[166:169], v[74:77]
	v_mfma_f32_16x16x32_bf16 v[70:73], v[6:9], v[186:189], v[70:73]
	v_mfma_f32_16x16x32_bf16 v[62:65], v[14:17], v[186:189], v[62:65]
	v_mfma_f32_16x16x32_bf16 v[54:57], v[6:9], v[206:209], v[54:57]
	v_mfma_f32_16x16x32_bf16 v[46:49], v[14:17], v[206:209], v[46:49]
	v_mfma_f32_16x16x32_bf16 v[2:5], v[6:9], v[226:229], v[2:5]
	v_mfma_f32_16x16x32_bf16 v[6:9], v[10:13], v[222:225], v[30:33]
	v_mfma_f32_16x16x32_bf16 v[6:9], v[14:17], v[226:229], v[6:9]
	s_setprio 0
	s_setprio 1
	v_mfma_f32_16x16x32_bf16 v[30:33], v[146:149], v[182:185], v[50:53]
	v_mfma_f32_16x16x32_bf16 v[50:53], v[150:153], v[186:189], v[30:33]
	v_mfma_f32_16x16x32_bf16 v[30:33], v[154:157], v[182:185], v[42:45]
	v_mfma_f32_16x16x32_bf16 v[42:45], v[158:161], v[186:189], v[30:33]
	v_mfma_f32_16x16x32_bf16 v[30:33], v[146:149], v[202:205], v[34:37]
	v_mfma_f32_16x16x32_bf16 v[26:29], v[154:157], v[202:205], v[26:29]
	v_mfma_f32_16x16x32_bf16 v[22:25], v[146:149], v[222:225], v[22:25]
	v_mfma_f32_16x16x32_bf16 v[18:21], v[154:157], v[222:225], v[18:21]
	v_mfma_f32_16x16x32_bf16 v[10:13], v[146:149], v[162:165], v[66:69]
	v_mfma_f32_16x16x32_bf16 v[14:17], v[154:157], v[162:165], v[58:61]
	v_mfma_f32_16x16x32_bf16 v[34:37], v[150:153], v[206:209], v[30:33]
	v_mfma_f32_16x16x32_bf16 v[26:29], v[158:161], v[206:209], v[26:29]
	s_setprio 3
	s_barrier
	v_mfma_f32_16x16x32_bf16 v[22:25], v[150:153], v[226:229], v[22:25]
	v_mfma_f32_16x16x32_bf16 v[18:21], v[158:161], v[226:229], v[18:21]
	v_mfma_f32_16x16x32_bf16 v[10:13], v[150:153], v[166:169], v[10:13]
	v_mfma_f32_16x16x32_bf16 v[14:17], v[158:161], v[166:169], v[14:17]
	s_setprio 0
	s_add_i32 s18, 0, 0x18000
	v_add_u32_e32 v0, s18, v191
	s_add_i32 s19, 0, 0x1c000
	ds_read_b128 v[30:33], v0
	ds_read_b128 v[38:41], v0 offset:1024
	ds_read_b128 v[58:61], v0 offset:2048
	ds_read_b128 v[66:69], v0 offset:3072
	v_add_u32_e32 v0, s19, v191
	ds_read_b128 v[146:149], v0
	ds_read_b128 v[150:153], v0 offset:1024
	ds_read_b128 v[154:157], v0 offset:2048
	ds_read_b128 v[158:161], v0 offset:3072
	s_add_u32 s8, s8, 0x40000
	s_addc_u32 s9, s9, 0
	s_mov_b32 m0, s69
	v_lshl_add_u64 v[250:251], s[8:9], 0, v[172:173]
	ds_read_b128 v[162:165], v200 offset:32768
	ds_read_b128 v[166:169], v200 offset:33792
	ds_read_b128 v[182:185], v200 offset:34816
	ds_read_b128 v[186:189], v200 offset:35840
	ds_read_b128 v[202:205], v200 offset:36864
	ds_read_b128 v[206:209], v200 offset:37888
	ds_read_b128 v[222:225], v200 offset:38912
	ds_read_b128 v[226:229], v200 offset:39936
	global_load_lds_dwordx4 v[250:251], off
	v_lshl_add_u64 v[250:251], s[8:9], 0, v[170:171]
	s_mov_b32 m0, s70
	s_nop 0
	global_load_lds_dwordx4 v[250:251], off
	s_waitcnt vmcnt(8)
	s_waitcnt lgkmcnt(0)
	s_barrier
	s_setprio 1
	v_mfma_f32_16x16x32_bf16 v[142:145], v[30:33], v[162:165], v[142:145]
	v_mfma_f32_16x16x32_bf16 v[142:145], v[38:41], v[166:169], v[142:145]
	v_mfma_f32_16x16x32_bf16 v[138:141], v[58:61], v[162:165], v[138:141]
	v_mfma_f32_16x16x32_bf16 v[138:141], v[66:69], v[166:169], v[138:141]
	v_mfma_f32_16x16x32_bf16 v[134:137], v[30:33], v[182:185], v[134:137]
	v_mfma_f32_16x16x32_bf16 v[134:137], v[38:41], v[186:189], v[134:137]
	v_mfma_f32_16x16x32_bf16 v[126:129], v[58:61], v[182:185], v[126:129]
	v_mfma_f32_16x16x32_bf16 v[126:129], v[66:69], v[186:189], v[126:129]
	v_mfma_f32_16x16x32_bf16 v[118:121], v[30:33], v[202:205], v[118:121]
	v_mfma_f32_16x16x32_bf16 v[118:121], v[38:41], v[206:209], v[118:121]
	v_mfma_f32_16x16x32_bf16 v[110:113], v[58:61], v[202:205], v[110:113]
	v_mfma_f32_16x16x32_bf16 v[110:113], v[66:69], v[206:209], v[110:113]
	v_mfma_f32_16x16x32_bf16 v[102:105], v[30:33], v[222:225], v[102:105]
	v_mfma_f32_16x16x32_bf16 v[102:105], v[38:41], v[226:229], v[102:105]
	v_mfma_f32_16x16x32_bf16 v[94:97], v[58:61], v[222:225], v[94:97]
	v_mfma_f32_16x16x32_bf16 v[94:97], v[66:69], v[226:229], v[94:97]
	s_setprio 0
	s_setprio 1
	v_mfma_f32_16x16x32_bf16 v[130:133], v[146:149], v[162:165], v[130:133]
	v_mfma_f32_16x16x32_bf16 v[130:133], v[150:153], v[166:169], v[130:133]
	v_mfma_f32_16x16x32_bf16 v[122:125], v[154:157], v[162:165], v[122:125]
	v_mfma_f32_16x16x32_bf16 v[122:125], v[158:161], v[166:169], v[122:125]
	v_mfma_f32_16x16x32_bf16 v[114:117], v[146:149], v[182:185], v[114:117]
	v_mfma_f32_16x16x32_bf16 v[114:117], v[150:153], v[186:189], v[114:117]
	v_mfma_f32_16x16x32_bf16 v[106:109], v[154:157], v[182:185], v[106:109]
	v_mfma_f32_16x16x32_bf16 v[106:109], v[158:161], v[186:189], v[106:109]
	v_mfma_f32_16x16x32_bf16 v[98:101], v[146:149], v[202:205], v[98:101]
	v_mfma_f32_16x16x32_bf16 v[98:101], v[150:153], v[206:209], v[98:101]
	v_mfma_f32_16x16x32_bf16 v[90:93], v[154:157], v[202:205], v[90:93]
	v_mfma_f32_16x16x32_bf16 v[90:93], v[158:161], v[206:209], v[90:93]
	s_setprio 3
	s_barrier
	v_mfma_f32_16x16x32_bf16 v[86:89], v[146:149], v[222:225], v[86:89]
	v_mfma_f32_16x16x32_bf16 v[86:89], v[150:153], v[226:229], v[86:89]
	v_mfma_f32_16x16x32_bf16 v[82:85], v[154:157], v[222:225], v[82:85]
	v_mfma_f32_16x16x32_bf16 v[82:85], v[158:161], v[226:229], v[82:85]
	s_setprio 0
	s_add_i32 s8, s18, s64
	v_lshl_add_u64 v[230:231], v[230:231], 0, s[22:23]
	s_mov_b32 m0, s8
	ds_read_b128 v[162:165], v200 offset:49152
	ds_read_b128 v[166:169], v200 offset:50176
	ds_read_b128 v[182:185], v200 offset:51200
	ds_read_b128 v[186:189], v200 offset:52224
	ds_read_b128 v[202:205], v200 offset:53248
	ds_read_b128 v[206:209], v200 offset:54272
	ds_read_b128 v[222:225], v200 offset:55296
	ds_read_b128 v[226:229], v200 offset:56320
	global_load_lds_dwordx4 v[230:231], off
	s_add_i32 m0, s8, 0x2000
	s_add_u32 s4, s4, 0x40080
	v_lshl_add_u64 v[230:231], v[232:233], 0, s[22:23]
	s_addc_u32 s5, s5, 0
	s_add_i32 s8, s19, s64
	global_load_lds_dwordx4 v[230:231], off
	v_lshl_add_u64 v[230:231], s[4:5], 0, v[172:173]
	s_mov_b32 m0, s8
	s_nop 0
	global_load_lds_dwordx4 v[230:231], off
	v_lshl_add_u64 v[230:231], s[4:5], 0, v[170:171]
	s_add_i32 m0, s8, 0x2000
	s_nop 0
	global_load_lds_dwordx4 v[230:231], off
	v_lshl_add_u64 v[230:231], v[246:247], 0, s[22:23]
	s_mov_b32 m0, s94
	s_nop 0
	global_load_lds_dwordx4 v[230:231], off
	v_lshl_add_u64 v[230:231], v[248:249], 0, s[22:23]
	s_mov_b32 m0, s95
	s_nop 0
	global_load_lds_dwordx4 v[230:231], off
	s_waitcnt vmcnt(8)
	s_waitcnt lgkmcnt(0)
	s_barrier
	s_setprio 1
	v_mfma_f32_16x16x32_bf16 v[78:81], v[30:33], v[162:165], v[78:81]
	v_mfma_f32_16x16x32_bf16 v[70:73], v[30:33], v[182:185], v[70:73]
	v_mfma_f32_16x16x32_bf16 v[54:57], v[30:33], v[202:205], v[54:57]
	v_mfma_f32_16x16x32_bf16 v[2:5], v[30:33], v[222:225], v[2:5]
	v_mfma_f32_16x16x32_bf16 v[78:81], v[38:41], v[166:169], v[78:81]
	v_mfma_f32_16x16x32_bf16 v[74:77], v[58:61], v[162:165], v[74:77]
	v_mfma_f32_16x16x32_bf16 v[70:73], v[38:41], v[186:189], v[70:73]
	v_mfma_f32_16x16x32_bf16 v[62:65], v[58:61], v[182:185], v[62:65]
	v_mfma_f32_16x16x32_bf16 v[54:57], v[38:41], v[206:209], v[54:57]
	v_mfma_f32_16x16x32_bf16 v[46:49], v[58:61], v[202:205], v[46:49]
	v_mfma_f32_16x16x32_bf16 v[38:41], v[38:41], v[226:229], v[2:5]
	v_mfma_f32_16x16x32_bf16 v[2:5], v[58:61], v[222:225], v[6:9]
	v_mfma_f32_16x16x32_bf16 v[74:77], v[66:69], v[166:169], v[74:77]
	v_mfma_f32_16x16x32_bf16 v[62:65], v[66:69], v[186:189], v[62:65]
	v_mfma_f32_16x16x32_bf16 v[46:49], v[66:69], v[206:209], v[46:49]
	v_mfma_f32_16x16x32_bf16 v[30:33], v[66:69], v[226:229], v[2:5]
	s_setprio 0
	s_setprio 1
	v_mfma_f32_16x16x32_bf16 v[2:5], v[146:149], v[162:165], v[10:13]
	v_mfma_f32_16x16x32_bf16 v[66:69], v[150:153], v[166:169], v[2:5]
	v_mfma_f32_16x16x32_bf16 v[2:5], v[154:157], v[162:165], v[14:17]
	v_mfma_f32_16x16x32_bf16 v[58:61], v[158:161], v[166:169], v[2:5]
	v_mfma_f32_16x16x32_bf16 v[2:5], v[146:149], v[182:185], v[50:53]
	v_mfma_f32_16x16x32_bf16 v[50:53], v[150:153], v[186:189], v[2:5]
	v_mfma_f32_16x16x32_bf16 v[2:5], v[154:157], v[182:185], v[42:45]
	v_mfma_f32_16x16x32_bf16 v[42:45], v[158:161], v[186:189], v[2:5]
	v_mfma_f32_16x16x32_bf16 v[2:5], v[146:149], v[202:205], v[34:37]
	v_mfma_f32_16x16x32_bf16 v[34:37], v[150:153], v[206:209], v[2:5]
	v_mfma_f32_16x16x32_bf16 v[2:5], v[154:157], v[202:205], v[26:29]
	v_mfma_f32_16x16x32_bf16 v[26:29], v[158:161], v[206:209], v[2:5]
	s_setprio 3
	s_barrier
	v_mfma_f32_16x16x32_bf16 v[2:5], v[146:149], v[222:225], v[22:25]
	v_mfma_f32_16x16x32_bf16 v[22:25], v[150:153], v[226:229], v[2:5]
	v_mfma_f32_16x16x32_bf16 v[2:5], v[154:157], v[222:225], v[18:21]
	v_mfma_f32_16x16x32_bf16 v[18:21], v[158:161], v[226:229], v[2:5]
	s_setprio 0
	s_add_i32 s17, s17, 2
	s_add_u32 s0, s0, 0x100
	s_addc_u32 s1, s1, 0
	s_add_u32 s14, s14, 0x100
	s_addc_u32 s15, s15, 0
	s_cmp_gt_u32 s17, 13
	s_cbranch_scc0 .LBB0_233
	s_and_b64 vcc, exec, s[78:79]
	s_cbranch_vccz .LBB0_236
	s_barrier

.LBB0_707:
	s_add_i32 s34, s68, 2
	s_add_u32 s35, s0, 0x80
	s_addc_u32 s69, s1, 0
	s_add_i32 s84, 0, 0x10000
	s_cmp_eq_u32 s96, s68
	s_cselect_b32 s69, s53, s69
	s_cselect_b32 s68, s52, s35
	s_cselect_b32 s89, s65, vcc_hi
	s_cselect_b32 s88, s64, vcc_lo
	s_add_i32 s35, 0, 0x14000
	v_add_u32_e32 v142, s84, v212
	v_add_u32_e32 v158, s35, v212
	ds_read_b128 v[130:133], v142
	ds_read_b128 v[134:137], v142 offset:1024
	ds_read_b128 v[138:141], v142 offset:2048
	ds_read_b128 v[142:145], v142 offset:3072
	ds_read_b128 v[146:149], v158
	ds_read_b128 v[150:153], v158 offset:1024
	ds_read_b128 v[154:157], v158 offset:2048
	ds_read_b128 v[158:161], v158 offset:3072
	v_lshl_add_u64 v[194:195], s[0:1], 0, v[224:225]
	s_add_i32 m0, s28, 0xc000
	ds_read_b128 v[162:165], v245
	ds_read_b128 v[166:169], v245 offset:1024
	ds_read_b128 v[170:173], v245 offset:2048
	ds_read_b128 v[174:177], v245 offset:3072
	ds_read_b128 v[178:181], v245 offset:4096
	ds_read_b128 v[182:185], v245 offset:5120
	ds_read_b128 v[186:189], v245 offset:6144
	ds_read_b128 v[190:193], v245 offset:7168
	global_load_lds_dwordx4 v[194:195], off
	v_lshl_add_u64 v[194:195], s[0:1], 0, v[226:227]
	s_add_i32 m0, s28, 0xe000
	s_nop 0
	global_load_lds_dwordx4 v[194:195], off
	s_waitcnt vmcnt(8)
	s_waitcnt lgkmcnt(0)
	s_barrier
	s_setprio 1
	v_mfma_f32_16x16x32_bf16 v[126:129], v[130:133], v[162:165], v[126:129]
	v_mfma_f32_16x16x32_bf16 v[126:129], v[134:137], v[166:169], v[126:129]
	v_mfma_f32_16x16x32_bf16 v[122:125], v[138:141], v[162:165], v[122:125]
	v_mfma_f32_16x16x32_bf16 v[122:125], v[142:145], v[166:169], v[122:125]
	v_mfma_f32_16x16x32_bf16 v[114:117], v[130:133], v[170:173], v[114:117]
	v_mfma_f32_16x16x32_bf16 v[114:117], v[134:137], v[174:177], v[114:117]
	v_mfma_f32_16x16x32_bf16 v[106:109], v[138:141], v[170:173], v[106:109]
	v_mfma_f32_16x16x32_bf16 v[106:109], v[142:145], v[174:177], v[106:109]
	v_mfma_f32_16x16x32_bf16 v[98:101], v[130:133], v[178:181], v[98:101]
	v_mfma_f32_16x16x32_bf16 v[98:101], v[134:137], v[182:185], v[98:101]
	v_mfma_f32_16x16x32_bf16 v[90:93], v[138:141], v[178:181], v[90:93]
	v_mfma_f32_16x16x32_bf16 v[90:93], v[142:145], v[182:185], v[90:93]
	v_mfma_f32_16x16x32_bf16 v[82:85], v[130:133], v[186:189], v[82:85]
	v_mfma_f32_16x16x32_bf16 v[82:85], v[134:137], v[190:193], v[82:85]
	v_mfma_f32_16x16x32_bf16 v[74:77], v[138:141], v[186:189], v[74:77]
	v_mfma_f32_16x16x32_bf16 v[74:77], v[142:145], v[190:193], v[74:77]
	s_setprio 0
	s_setprio 1
	v_mfma_f32_16x16x32_bf16 v[118:121], v[146:149], v[162:165], v[118:121]
	v_mfma_f32_16x16x32_bf16 v[118:121], v[150:153], v[166:169], v[118:121]
	v_mfma_f32_16x16x32_bf16 v[110:113], v[154:157], v[162:165], v[110:113]
	v_mfma_f32_16x16x32_bf16 v[110:113], v[158:161], v[166:169], v[110:113]
	v_mfma_f32_16x16x32_bf16 v[102:105], v[146:149], v[170:173], v[102:105]
	v_mfma_f32_16x16x32_bf16 v[102:105], v[150:153], v[174:177], v[102:105]
	v_mfma_f32_16x16x32_bf16 v[94:97], v[154:157], v[170:173], v[94:97]
	v_mfma_f32_16x16x32_bf16 v[94:97], v[158:161], v[174:177], v[94:97]
	v_mfma_f32_16x16x32_bf16 v[86:89], v[146:149], v[178:181], v[86:89]
	v_mfma_f32_16x16x32_bf16 v[86:89], v[150:153], v[182:185], v[86:89]
	v_mfma_f32_16x16x32_bf16 v[78:81], v[154:157], v[178:181], v[78:81]
	v_mfma_f32_16x16x32_bf16 v[78:81], v[158:161], v[182:185], v[78:81]
	s_setprio 3
	s_barrier
	v_mfma_f32_16x16x32_bf16 v[70:73], v[146:149], v[186:189], v[70:73]
	v_mfma_f32_16x16x32_bf16 v[70:73], v[150:153], v[190:193], v[70:73]
	v_mfma_f32_16x16x32_bf16 v[66:69], v[154:157], v[186:189], v[66:69]
	v_mfma_f32_16x16x32_bf16 v[66:69], v[158:161], v[190:193], v[66:69]
	s_setprio 0
	s_add_i32 s84, s84, s19
	v_lshl_add_u64 v[194:195], s[88:89], 0, v[0:1]
	s_mov_b32 m0, s84
	ds_read_b128 v[162:165], v245 offset:16384
	ds_read_b128 v[166:169], v245 offset:17408
	ds_read_b128 v[170:173], v245 offset:18432
	ds_read_b128 v[174:177], v245 offset:19456
	ds_read_b128 v[178:181], v245 offset:20480
	ds_read_b128 v[182:185], v245 offset:21504
	ds_read_b128 v[186:189], v245 offset:22528
	ds_read_b128 v[190:193], v245 offset:23552
	global_load_lds_dwordx4 v[194:195], off
	s_add_i32 m0, s84, 0x2000
	v_lshl_add_u64 v[196:197], s[88:89], 0, v[222:223]
	s_add_u32 s88, s88, s2
	s_addc_u32 s89, s89, 0
	s_add_i32 s35, s35, s19
	global_load_lds_dwordx4 v[196:197], off
	v_lshl_add_u64 v[198:199], s[88:89], 0, v[0:1]
	s_mov_b32 m0, s35
	v_lshl_add_u64 v[200:201], s[88:89], 0, v[222:223]
	global_load_lds_dwordx4 v[198:199], off
	s_add_i32 m0, s35, 0x2000
	v_lshl_add_u64 v[202:203], s[68:69], 0, v[0:1]
	global_load_lds_dwordx4 v[200:201], off
	s_mov_b32 m0, s28
	v_lshl_add_u64 v[204:205], s[68:69], 0, v[222:223]
	global_load_lds_dwordx4 v[202:203], off
	s_mov_b32 m0, s29
	s_nop 0
	global_load_lds_dwordx4 v[204:205], off
	s_waitcnt vmcnt(8)
	s_waitcnt lgkmcnt(0)
	s_barrier
	s_setprio 1
	v_mfma_f32_16x16x32_bf16 v[62:65], v[130:133], v[162:165], v[62:65]
	v_mfma_f32_16x16x32_bf16 v[62:65], v[134:137], v[166:169], v[62:65]
	v_mfma_f32_16x16x32_bf16 v[58:61], v[138:141], v[162:165], v[58:61]
	v_mfma_f32_16x16x32_bf16 v[58:61], v[142:145], v[166:169], v[58:61]
	v_mfma_f32_16x16x32_bf16 v[50:53], v[130:133], v[170:173], v[50:53]
	v_mfma_f32_16x16x32_bf16 v[50:53], v[134:137], v[174:177], v[50:53]
	v_mfma_f32_16x16x32_bf16 v[42:45], v[138:141], v[170:173], v[42:45]
	v_mfma_f32_16x16x32_bf16 v[42:45], v[142:145], v[174:177], v[42:45]
	v_mfma_f32_16x16x32_bf16 v[34:37], v[130:133], v[178:181], v[34:37]
	v_mfma_f32_16x16x32_bf16 v[34:37], v[134:137], v[182:185], v[34:37]
	v_mfma_f32_16x16x32_bf16 v[26:29], v[138:141], v[178:181], v[26:29]
	v_mfma_f32_16x16x32_bf16 v[26:29], v[142:145], v[182:185], v[26:29]
	v_mfma_f32_16x16x32_bf16 v[18:21], v[130:133], v[186:189], v[18:21]
	v_mfma_f32_16x16x32_bf16 v[18:21], v[134:137], v[190:193], v[18:21]
	v_mfma_f32_16x16x32_bf16 v[10:13], v[138:141], v[186:189], v[10:13]
	v_mfma_f32_16x16x32_bf16 v[10:13], v[142:145], v[190:193], v[10:13]
	s_setprio 0
	s_setprio 1
	v_mfma_f32_16x16x32_bf16 v[54:57], v[146:149], v[162:165], v[54:57]
	v_mfma_f32_16x16x32_bf16 v[54:57], v[150:153], v[166:169], v[54:57]
	v_mfma_f32_16x16x32_bf16 v[46:49], v[154:157], v[162:165], v[46:49]
	v_mfma_f32_16x16x32_bf16 v[46:49], v[158:161], v[166:169], v[46:49]
	v_mfma_f32_16x16x32_bf16 v[38:41], v[146:149], v[170:173], v[38:41]
	v_mfma_f32_16x16x32_bf16 v[38:41], v[150:153], v[174:177], v[38:41]
	v_mfma_f32_16x16x32_bf16 v[30:33], v[154:157], v[170:173], v[30:33]
	v_mfma_f32_16x16x32_bf16 v[30:33], v[158:161], v[174:177], v[30:33]
	v_mfma_f32_16x16x32_bf16 v[22:25], v[146:149], v[178:181], v[22:25]
	v_mfma_f32_16x16x32_bf16 v[22:25], v[150:153], v[182:185], v[22:25]
	v_mfma_f32_16x16x32_bf16 v[14:17], v[154:157], v[178:181], v[14:17]
	v_mfma_f32_16x16x32_bf16 v[14:17], v[158:161], v[182:185], v[14:17]
	s_setprio 3
	s_barrier
	v_mfma_f32_16x16x32_bf16 v[6:9], v[146:149], v[186:189], v[6:9]
	v_mfma_f32_16x16x32_bf16 v[6:9], v[150:153], v[190:193], v[6:9]
	v_mfma_f32_16x16x32_bf16 v[2:5], v[154:157], v[186:189], v[2:5]
	v_mfma_f32_16x16x32_bf16 v[2:5], v[158:161], v[190:193], v[2:5]
	s_setprio 0
	s_add_i32 s35, 0, 0x18000
	s_add_i32 s84, 0, 0x1c000
	v_add_u32_e32 v142, s35, v212
	v_add_u32_e32 v158, s84, v212
	ds_read_b128 v[130:133], v142
	ds_read_b128 v[134:137], v142 offset:1024
	ds_read_b128 v[138:141], v142 offset:2048
	ds_read_b128 v[142:145], v142 offset:3072
	ds_read_b128 v[146:149], v158
	ds_read_b128 v[150:153], v158 offset:1024
	ds_read_b128 v[154:157], v158 offset:2048
	ds_read_b128 v[158:161], v158 offset:3072
	s_add_u32 s68, s68, s2
	s_addc_u32 s69, s69, 0
	s_mov_b32 m0, s25
	v_lshl_add_u64 v[206:207], s[68:69], 0, v[0:1]
	ds_read_b128 v[162:165], v245 offset:32768
	ds_read_b128 v[166:169], v245 offset:33792
	ds_read_b128 v[170:173], v245 offset:34816
	ds_read_b128 v[174:177], v245 offset:35840
	ds_read_b128 v[178:181], v245 offset:36864
	ds_read_b128 v[182:185], v245 offset:37888
	ds_read_b128 v[186:189], v245 offset:38912
	ds_read_b128 v[190:193], v245 offset:39936
	global_load_lds_dwordx4 v[206:207], off
	v_lshl_add_u64 v[206:207], s[68:69], 0, v[222:223]
	s_mov_b32 m0, s36
	s_nop 0
	global_load_lds_dwordx4 v[206:207], off
	s_waitcnt vmcnt(8)
	s_waitcnt lgkmcnt(0)
	s_barrier
	s_setprio 1
	v_mfma_f32_16x16x32_bf16 v[126:129], v[130:133], v[162:165], v[126:129]
	v_mfma_f32_16x16x32_bf16 v[126:129], v[134:137], v[166:169], v[126:129]
	v_mfma_f32_16x16x32_bf16 v[122:125], v[138:141], v[162:165], v[122:125]
	v_mfma_f32_16x16x32_bf16 v[122:125], v[142:145], v[166:169], v[122:125]
	v_mfma_f32_16x16x32_bf16 v[114:117], v[130:133], v[170:173], v[114:117]
	v_mfma_f32_16x16x32_bf16 v[114:117], v[134:137], v[174:177], v[114:117]
	v_mfma_f32_16x16x32_bf16 v[106:109], v[138:141], v[170:173], v[106:109]
	v_mfma_f32_16x16x32_bf16 v[106:109], v[142:145], v[174:177], v[106:109]
	v_mfma_f32_16x16x32_bf16 v[98:101], v[130:133], v[178:181], v[98:101]
	v_mfma_f32_16x16x32_bf16 v[98:101], v[134:137], v[182:185], v[98:101]
	v_mfma_f32_16x16x32_bf16 v[90:93], v[138:141], v[178:181], v[90:93]
	v_mfma_f32_16x16x32_bf16 v[90:93], v[142:145], v[182:185], v[90:93]
	v_mfma_f32_16x16x32_bf16 v[82:85], v[130:133], v[186:189], v[82:85]
	v_mfma_f32_16x16x32_bf16 v[82:85], v[134:137], v[190:193], v[82:85]
	v_mfma_f32_16x16x32_bf16 v[74:77], v[138:141], v[186:189], v[74:77]
	v_mfma_f32_16x16x32_bf16 v[74:77], v[142:145], v[190:193], v[74:77]
	s_setprio 0
	s_setprio 1
	v_mfma_f32_16x16x32_bf16 v[118:121], v[146:149], v[162:165], v[118:121]
	v_mfma_f32_16x16x32_bf16 v[118:121], v[150:153], v[166:169], v[118:121]
	v_mfma_f32_16x16x32_bf16 v[110:113], v[154:157], v[162:165], v[110:113]
	v_mfma_f32_16x16x32_bf16 v[110:113], v[158:161], v[166:169], v[110:113]
	v_mfma_f32_16x16x32_bf16 v[102:105], v[146:149], v[170:173], v[102:105]
	v_mfma_f32_16x16x32_bf16 v[102:105], v[150:153], v[174:177], v[102:105]
	v_mfma_f32_16x16x32_bf16 v[94:97], v[154:157], v[170:173], v[94:97]
	v_mfma_f32_16x16x32_bf16 v[94:97], v[158:161], v[174:177], v[94:97]
	v_mfma_f32_16x16x32_bf16 v[86:89], v[146:149], v[178:181], v[86:89]
	v_mfma_f32_16x16x32_bf16 v[86:89], v[150:153], v[182:185], v[86:89]
	v_mfma_f32_16x16x32_bf16 v[78:81], v[154:157], v[178:181], v[78:81]
	v_mfma_f32_16x16x32_bf16 v[78:81], v[158:161], v[182:185], v[78:81]
	s_setprio 3
	s_barrier
	v_mfma_f32_16x16x32_bf16 v[70:73], v[146:149], v[186:189], v[70:73]
	v_mfma_f32_16x16x32_bf16 v[70:73], v[150:153], v[190:193], v[70:73]
	v_mfma_f32_16x16x32_bf16 v[66:69], v[154:157], v[186:189], v[66:69]
	v_mfma_f32_16x16x32_bf16 v[66:69], v[158:161], v[190:193], v[66:69]
	s_setprio 0
	s_add_i32 s35, s35, s19
	v_lshl_add_u64 v[194:195], v[194:195], 0, s[22:23]
	s_mov_b32 m0, s35
	ds_read_b128 v[162:165], v245 offset:49152
	ds_read_b128 v[166:169], v245 offset:50176
	ds_read_b128 v[170:173], v245 offset:51200
	ds_read_b128 v[174:177], v245 offset:52224
	ds_read_b128 v[178:181], v245 offset:53248
	ds_read_b128 v[182:185], v245 offset:54272
	ds_read_b128 v[186:189], v245 offset:55296
	ds_read_b128 v[190:193], v245 offset:56320
	global_load_lds_dwordx4 v[194:195], off
	v_lshl_add_u64 v[194:195], v[196:197], 0, s[22:23]
	s_add_i32 m0, s35, 0x2000
	s_add_i32 s35, s84, s19
	global_load_lds_dwordx4 v[194:195], off
	v_lshl_add_u64 v[194:195], v[198:199], 0, s[22:23]
	s_mov_b32 m0, s35
	s_nop 0
	global_load_lds_dwordx4 v[194:195], off
	v_lshl_add_u64 v[194:195], v[200:201], 0, s[22:23]
	s_add_i32 m0, s35, 0x2000
	s_nop 0
	global_load_lds_dwordx4 v[194:195], off
	v_lshl_add_u64 v[194:195], v[202:203], 0, s[22:23]
	s_mov_b32 m0, s37
	s_nop 0
	global_load_lds_dwordx4 v[194:195], off
	v_lshl_add_u64 v[194:195], v[204:205], 0, s[22:23]
	s_mov_b32 m0, s40
	s_nop 0
	global_load_lds_dwordx4 v[194:195], off
	s_waitcnt vmcnt(8)
	s_waitcnt lgkmcnt(0)
	s_barrier
	s_setprio 1
	v_mfma_f32_16x16x32_bf16 v[62:65], v[130:133], v[162:165], v[62:65]
	v_mfma_f32_16x16x32_bf16 v[62:65], v[134:137], v[166:169], v[62:65]
	v_mfma_f32_16x16x32_bf16 v[58:61], v[138:141], v[162:165], v[58:61]
	v_mfma_f32_16x16x32_bf16 v[58:61], v[142:145], v[166:169], v[58:61]
	v_mfma_f32_16x16x32_bf16 v[50:53], v[130:133], v[170:173], v[50:53]
	v_mfma_f32_16x16x32_bf16 v[50:53], v[134:137], v[174:177], v[50:53]
	v_mfma_f32_16x16x32_bf16 v[42:45], v[138:141], v[170:173], v[42:45]
	v_mfma_f32_16x16x32_bf16 v[42:45], v[142:145], v[174:177], v[42:45]
	v_mfma_f32_16x16x32_bf16 v[34:37], v[130:133], v[178:181], v[34:37]
	v_mfma_f32_16x16x32_bf16 v[34:37], v[134:137], v[182:185], v[34:37]
	v_mfma_f32_16x16x32_bf16 v[26:29], v[138:141], v[178:181], v[26:29]
	v_mfma_f32_16x16x32_bf16 v[26:29], v[142:145], v[182:185], v[26:29]
	v_mfma_f32_16x16x32_bf16 v[18:21], v[130:133], v[186:189], v[18:21]
	v_mfma_f32_16x16x32_bf16 v[18:21], v[134:137], v[190:193], v[18:21]
	v_mfma_f32_16x16x32_bf16 v[10:13], v[138:141], v[186:189], v[10:13]
	v_mfma_f32_16x16x32_bf16 v[10:13], v[142:145], v[190:193], v[10:13]
	s_setprio 0
	s_setprio 1
	v_mfma_f32_16x16x32_bf16 v[54:57], v[146:149], v[162:165], v[54:57]
	v_mfma_f32_16x16x32_bf16 v[54:57], v[150:153], v[166:169], v[54:57]
	v_mfma_f32_16x16x32_bf16 v[46:49], v[154:157], v[162:165], v[46:49]
	v_mfma_f32_16x16x32_bf16 v[46:49], v[158:161], v[166:169], v[46:49]
	v_mfma_f32_16x16x32_bf16 v[38:41], v[146:149], v[170:173], v[38:41]
	v_mfma_f32_16x16x32_bf16 v[38:41], v[150:153], v[174:177], v[38:41]
	v_mfma_f32_16x16x32_bf16 v[30:33], v[154:157], v[170:173], v[30:33]
	v_mfma_f32_16x16x32_bf16 v[30:33], v[158:161], v[174:177], v[30:33]
	v_mfma_f32_16x16x32_bf16 v[22:25], v[146:149], v[178:181], v[22:25]
	v_mfma_f32_16x16x32_bf16 v[22:25], v[150:153], v[182:185], v[22:25]
	v_mfma_f32_16x16x32_bf16 v[14:17], v[154:157], v[178:181], v[14:17]
	v_mfma_f32_16x16x32_bf16 v[14:17], v[158:161], v[182:185], v[14:17]
	s_setprio 3
	s_barrier
	v_mfma_f32_16x16x32_bf16 v[6:9], v[146:149], v[186:189], v[6:9]
	v_mfma_f32_16x16x32_bf16 v[6:9], v[150:153], v[190:193], v[6:9]
	v_mfma_f32_16x16x32_bf16 v[2:5], v[154:157], v[186:189], v[2:5]
	v_mfma_f32_16x16x32_bf16 v[2:5], v[158:161], v[190:193], v[2:5]
	s_setprio 0
	s_add_u32 s0, s0, 0x100
	s_addc_u32 s1, s1, 0
	s_add_u32 vcc_lo, vcc_lo, 0x100
	s_addc_u32 vcc_hi, vcc_hi, 0
	s_cmp_ge_u32 s34, s18
	s_mov_b32 s68, s34
	s_cbranch_scc0 .LBB0_707
	s_and_b64 vcc, exec, s[50:51]
	s_cbranch_vccz .LBB0_710
	s_barrier
